# attention early exit when every row tail sum >= 128 (exp2 arg < -126 flushes to exact 0 in v_exp_f32) instead of 192
# speedup vs baseline: 1.0075x; 1.0075x over previous
; #define LAS __attribute__((address_space(3)))
; __device__ __forceinline__ void attn_unit(LAS unsigned char* lds, const int wid, int b, int h, int qb, const bf16_t* __restrict__ Q, const bf16_t* __restrict__ K,
;                                           const bf16_t* __restrict__ V, const bf16_t* __restrict__ ZS, bf16_t* __restrict__ OG) {
;     ...
;     for (int t = NT - 1; t >= 0; --t) {
;         if (t > 0) ATT_STAGE(t - 1, (kcur ^ 1) * 16384, 32768 + vnext * 16384);
;         const LAS unsigned char* kb = lds + kcur * 16384;
;         const LAS unsigned char* vbp = lds + 32768 + vprev * 16384;
;         const int k0 = 64 * t;
;         const bool valid = (k0 < qw0 + 31);
;         if (valid) {
;             if (prev_valid) attn_tile<true>(kb, vbp, qf, o, pa, carry, koff, vbase, vcq, k0, qw0, qabs, hi);
;             else            attn_tile<false>(kb, vbp, qf, o, pa, carry, koff, vbase, vcq, k0, qw0, qabs, hi);
;         }
;         prev_valid = valid;
;         asm volatile("s_waitcnt vmcnt(0)" ::: "memory");
;         __syncthreads();
;         kcur ^= 1; { const int tmp = vprev; vprev = vcur; vcur = vnext; vnext = tmp; }
;     }
.LBB0_609:
	s_waitcnt vmcnt(0)
	s_xor_b32 s67, s67, 1
	s_add_i32 s42, s42, -1
	s_sub_i32 s65, s65, 64
	v_cmp_gt_f32_e32 vcc, 0x43000000, v158
	s_lshr_b32 s98, s54, 3
	s_lshl_b32 s99, s67, 5
	s_add_i32 s98, s98, s99
	s_add_i32 s98, s98, 0x24000
	s_cmp_lg_u64 vcc, 0
	s_cselect_b32 s99, 1, 0
	v_mov_b32_e32 v80, s98
	v_mov_b32_e32 v81, s99
	s_mov_b64 s[100:101], exec
	s_mov_b64 exec, 1
	ds_write_b32 v80, v81
	s_mov_b64 exec, s[100:101]
	s_cmpk_lg_i32 s65, 0xffc0
	s_waitcnt vmcnt(0) lgkmcnt(0)
	s_barrier
	s_cbranch_scc0 .LBB0_611
	s_lshl_b32 s98, s67, 5
	s_add_i32 s98, s98, 0x24000
	v_mov_b32_e32 v80, s98
	ds_read_b128 v[84:87], v80
	ds_read_b128 v[88:91], v80 offset:16
	s_waitcnt lgkmcnt(0)
	v_or3_b32 v84, v84, v85, v86
	v_or3_b32 v88, v88, v89, v90
	v_or3_b32 v84, v84, v87, v91
	v_or_b32_e32 v84, v84, v88
	s_nop 0
	v_readfirstlane_b32 s99, v84
	s_cmp_eq_u32 s99, 0
	s_cbranch_scc1 .LBB0_611
	s_mov_b32 s6, s71
	s_mov_b32 s71, s72
	s_mov_b32 s72, s73
	s_mov_b64 s[4:5], s[52:53]
	s_mov_b32 s73, s6
	s_cmp_lg_u32 s65, 0
	s_mov_b64 s[6:7], -1
	s_cbranch_scc1 .LBB0_595
	s_branch .LBB0_596

; #define LAS __attribute__((address_space(3)))
; __device__ __forceinline__ void attn_unit(LAS unsigned char* lds, const int wid, int b, int h, int qb, const bf16_t* __restrict__ Q, const bf16_t* __restrict__ K,
;                                           const bf16_t* __restrict__ V, const bf16_t* __restrict__ ZS, bf16_t* __restrict__ OG) {
;     ...
;     for (int t = NT - 1; t >= 0; --t) {
;         if (t > 0) ATT_STAGE(t - 1, (kcur ^ 1) * 16384, 32768 + vnext * 16384);
;         const LAS unsigned char* kb = lds + kcur * 16384;
;         const LAS unsigned char* vbp = lds + 32768 + vprev * 16384;
;         const int k0 = 64 * t;
;         const bool valid = (k0 < qw0 + 31);
;         if (valid) {
;             if (prev_valid) attn_tile<true>(kb, vbp, qf, o, pa, carry, koff, vbase, vcq, k0, qw0, qabs, hi);
;             else            attn_tile<false>(kb, vbp, qf, o, pa, carry, koff, vbase, vcq, k0, qw0, qabs, hi);
;         }
;         prev_valid = valid;
;         asm volatile("s_waitcnt vmcnt(0)" ::: "memory");
;         __syncthreads();
;         kcur ^= 1; { const int tmp = vprev; vprev = vcur; vcur = vnext; vnext = tmp; }
;     }
.LBB0_626:
	s_waitcnt vmcnt(0)
	s_xor_b32 s67, s67, 1
	s_add_i32 s42, s42, -1
	s_sub_i32 s66, s66, 64
	v_cmp_gt_f32_e32 vcc, 0x43000000, v158
	s_lshr_b32 s98, s54, 3
	s_lshl_b32 s99, s67, 5
	s_add_i32 s98, s98, s99
	s_add_i32 s98, s98, 0x24000
	s_cmp_lg_u64 vcc, 0
	s_cselect_b32 s99, 1, 0
	v_mov_b32_e32 v80, s98
	v_mov_b32_e32 v81, s99
	s_mov_b64 s[100:101], exec
	s_mov_b64 exec, 1
	ds_write_b32 v80, v81
	s_mov_b64 exec, s[100:101]
	s_cmp_lg_u32 s42, -2
	s_waitcnt vmcnt(0) lgkmcnt(0)
	s_barrier
	s_cbranch_scc0 .LBB0_593
	s_lshl_b32 s98, s67, 5
	s_add_i32 s98, s98, 0x24000
	v_mov_b32_e32 v80, s98
	ds_read_b128 v[84:87], v80
	ds_read_b128 v[88:91], v80 offset:16
	s_waitcnt lgkmcnt(0)
	v_or3_b32 v84, v84, v85, v86
	v_or3_b32 v88, v88, v89, v90
	v_or3_b32 v84, v84, v87, v91
	v_or_b32_e32 v84, v84, v88
	s_nop 0
	v_readfirstlane_b32 s99, v84
	s_cmp_eq_u32 s99, 0
	s_cbranch_scc1 .LBB0_593
	s_mov_b32 s6, s71
	s_mov_b32 s71, s64
	s_mov_b32 s64, s72
	s_mov_b64 s[4:5], s[52:53]
	s_mov_b32 s72, s6
	s_cmp_lg_u32 s42, -1
	s_mov_b64 s[6:7], -1
	s_cbranch_scc1 .LBB0_612
	s_branch .LBB0_613
